# grid-barrier wait loops without the 64-cycle sleeps as well
# baseline (speedup 1.0000x reference)
.LBB0_46:
	global_load_dword v16, v17, s[6:7] offset:1024 sc1
	global_load_dword v1, v17, s[6:7] offset:1280 sc1
	global_load_dword v2, v17, s[6:7] offset:1536 sc1
	global_load_dword v3, v17, s[6:7] offset:1792 sc1
	global_load_dword v4, v17, s[6:7] offset:2048 sc1
	global_load_dword v5, v17, s[6:7] offset:2304 sc1
	global_load_dword v6, v17, s[6:7] offset:2560 sc1
	global_load_dword v7, v17, s[6:7] offset:2816 sc1
	global_load_dword v8, v17, s[6:7] offset:3072 sc1
	global_load_dword v9, v17, s[6:7] offset:3328 sc1
	global_load_dword v10, v17, s[6:7] offset:3584 sc1
	global_load_dword v11, v17, s[6:7] offset:3840 sc1
	global_load_dword v12, v17, s[8:9] sc1
	global_load_dword v13, v17, s[10:11] sc1
	global_load_dword v14, v17, s[12:13] sc1
	global_load_dword v15, v17, s[14:15] sc1
	s_mov_b64 s[16:17], -1
	s_mov_b64 s[18:19], -1
	s_waitcnt vmcnt(14)
	v_add_u32_e32 v18, v1, v16
	s_waitcnt vmcnt(13)
	v_add_u32_e32 v18, v18, v2
	s_waitcnt vmcnt(12)
	v_add_u32_e32 v18, v18, v3
	s_waitcnt vmcnt(11)
	v_add_u32_e32 v18, v18, v4
	s_waitcnt vmcnt(10)
	v_add_u32_e32 v18, v18, v5
	s_waitcnt vmcnt(9)
	v_add_u32_e32 v18, v18, v6
	s_waitcnt vmcnt(8)
	v_add_u32_e32 v18, v18, v7
	s_waitcnt vmcnt(7)
	v_add_u32_e32 v18, v18, v8
	s_waitcnt vmcnt(6)
	v_add_u32_e32 v18, v18, v9
	s_waitcnt vmcnt(5)
	v_add_u32_e32 v18, v18, v10
	s_waitcnt vmcnt(4)
	v_add_u32_e32 v18, v18, v11
	s_waitcnt vmcnt(3)
	v_add_u32_e32 v18, v18, v12
	s_waitcnt vmcnt(2)
	v_add_u32_e32 v18, v18, v13
	s_waitcnt vmcnt(1)
	v_add_u32_e32 v18, v18, v14
	s_waitcnt vmcnt(0)
	v_add_u32_e32 v18, v18, v15
	v_cmp_eq_u32_e32 vcc, s22, v18
	s_cbranch_vccnz .LBB0_45
	s_and_b32 s16, s23, 0xff
	s_cmp_eq_u32 s16, 0
	s_mov_b64 s[16:17], -1
	s_mov_b64 s[20:21], -1
	s_nop 0
	s_cbranch_scc0 .LBB0_50
	global_load_dword v18, v17, s[6:7] offset:512 sc1
	s_waitcnt vmcnt(0)
	v_cmp_eq_u32_e32 vcc, 0, v18
	s_cbranch_vccnz .LBB0_52
	s_mov_b64 s[20:21], 0

.LBB0_83:
	s_and_b32 s18, s22, 0xff
	s_mov_b64 s[16:17], -1
	s_cmp_lg_u32 s18, 0
	s_mov_b64 s[20:21], -1
	s_nop 0
	s_cbranch_scc1 .LBB0_86
	global_load_dword v2, v1, s[8:9] offset:512 sc1
	s_waitcnt vmcnt(0)
	v_cmp_eq_u32_e32 vcc, 0, v2
	s_cbranch_vccnz .LBB0_88
	s_mov_b64 s[20:21], 0
	s_mov_b64 s[18:19], -1

.LBB0_97:
	s_and_b32 s16, s20, 0xff
	s_mov_b64 s[14:15], -1
	s_cmp_lg_u32 s16, 0
	s_mov_b64 s[18:19], -1
	s_nop 0
	s_cbranch_scc1 .LBB0_100
	global_load_dword v3, v2, s[0:1] offset:512 sc1
	s_waitcnt vmcnt(0)
	v_cmp_eq_u32_e32 vcc, 0, v3
	s_cbranch_vccnz .LBB0_102
	s_mov_b64 s[18:19], 0
	s_mov_b64 s[16:17], -1

.LBB0_139:
	global_load_dword v16, v17, s[6:7] offset:1024 sc1
	global_load_dword v1, v17, s[6:7] offset:1280 sc1
	global_load_dword v2, v17, s[6:7] offset:1536 sc1
	global_load_dword v3, v17, s[6:7] offset:1792 sc1
	global_load_dword v4, v17, s[6:7] offset:2048 sc1
	global_load_dword v5, v17, s[6:7] offset:2304 sc1
	global_load_dword v6, v17, s[6:7] offset:2560 sc1
	global_load_dword v7, v17, s[6:7] offset:2816 sc1
	global_load_dword v8, v17, s[6:7] offset:3072 sc1
	global_load_dword v9, v17, s[6:7] offset:3328 sc1
	global_load_dword v10, v17, s[6:7] offset:3584 sc1
	global_load_dword v11, v17, s[6:7] offset:3840 sc1
	global_load_dword v12, v17, s[8:9] sc1
	global_load_dword v13, v17, s[10:11] sc1
	global_load_dword v14, v17, s[12:13] sc1
	global_load_dword v15, v17, s[14:15] sc1
	s_mov_b64 s[18:19], -1
	s_mov_b64 s[22:23], -1
	s_waitcnt vmcnt(14)
	v_add_u32_e32 v18, v1, v16
	s_waitcnt vmcnt(13)
	v_add_u32_e32 v18, v18, v2
	s_waitcnt vmcnt(12)
	v_add_u32_e32 v18, v18, v3
	s_waitcnt vmcnt(11)
	v_add_u32_e32 v18, v18, v4
	s_waitcnt vmcnt(10)
	v_add_u32_e32 v18, v18, v5
	s_waitcnt vmcnt(9)
	v_add_u32_e32 v18, v18, v6
	s_waitcnt vmcnt(8)
	v_add_u32_e32 v18, v18, v7
	s_waitcnt vmcnt(7)
	v_add_u32_e32 v18, v18, v8
	s_waitcnt vmcnt(6)
	v_add_u32_e32 v18, v18, v9
	s_waitcnt vmcnt(5)
	v_add_u32_e32 v18, v18, v10
	s_waitcnt vmcnt(4)
	v_add_u32_e32 v18, v18, v11
	s_waitcnt vmcnt(3)
	v_add_u32_e32 v18, v18, v12
	s_waitcnt vmcnt(2)
	v_add_u32_e32 v18, v18, v13
	s_waitcnt vmcnt(1)
	v_add_u32_e32 v18, v18, v14
	s_waitcnt vmcnt(0)
	v_add_u32_e32 v18, v18, v15
	v_cmp_eq_u32_e32 vcc, s26, v18
	s_cbranch_vccnz .LBB0_138
	s_and_b32 s18, s27, 0xff
	s_cmp_eq_u32 s18, 0
	s_mov_b64 s[18:19], -1
	s_mov_b64 s[24:25], -1
	s_nop 0
	s_cbranch_scc0 .LBB0_143
	global_load_dword v18, v17, s[6:7] offset:512 sc1
	s_waitcnt vmcnt(0)
	v_cmp_eq_u32_e32 vcc, 0, v18
	s_cbranch_vccnz .LBB0_145
	s_mov_b64 s[24:25], 0

.LBB0_171:
	s_and_b32 s22, s26, 0xff
	s_mov_b64 s[18:19], -1
	s_cmp_lg_u32 s22, 0
	s_mov_b64 s[24:25], -1
	s_nop 0
	s_cbranch_scc1 .LBB0_174
	global_load_dword v2, v1, s[8:9] offset:512 sc1
	s_waitcnt vmcnt(0)
	v_cmp_eq_u32_e32 vcc, 0, v2
	s_cbranch_vccnz .LBB0_176
	s_mov_b64 s[24:25], 0
	s_mov_b64 s[22:23], -1

.LBB0_185:
	s_and_b32 s18, s24, 0xff
	s_mov_b64 s[14:15], -1
	s_cmp_lg_u32 s18, 0
	s_mov_b64 s[22:23], -1
	s_nop 0
	s_cbranch_scc1 .LBB0_188
	global_load_dword v2, v1, s[0:1] offset:512 sc1
	s_waitcnt vmcnt(0)
	v_cmp_eq_u32_e32 vcc, 0, v2
	s_cbranch_vccnz .LBB0_190
	s_mov_b64 s[22:23], 0
	s_mov_b64 s[18:19], -1

.LBB0_244:
	global_load_dword v16, v17, s[6:7] offset:1024 sc1
	global_load_dword v1, v17, s[6:7] offset:1280 sc1
	global_load_dword v2, v17, s[6:7] offset:1536 sc1
	global_load_dword v3, v17, s[6:7] offset:1792 sc1
	global_load_dword v4, v17, s[6:7] offset:2048 sc1
	global_load_dword v5, v17, s[6:7] offset:2304 sc1
	global_load_dword v6, v17, s[6:7] offset:2560 sc1
	global_load_dword v7, v17, s[6:7] offset:2816 sc1
	global_load_dword v8, v17, s[6:7] offset:3072 sc1
	global_load_dword v9, v17, s[6:7] offset:3328 sc1
	global_load_dword v10, v17, s[6:7] offset:3584 sc1
	global_load_dword v11, v17, s[6:7] offset:3840 sc1
	global_load_dword v12, v17, s[8:9] sc1
	global_load_dword v13, v17, s[10:11] sc1
	global_load_dword v14, v17, s[18:19] sc1
	global_load_dword v15, v17, s[22:23] sc1
	s_mov_b64 s[24:25], -1
	s_mov_b64 s[26:27], -1
	s_waitcnt vmcnt(14)
	v_add_u32_e32 v18, v1, v16
	s_waitcnt vmcnt(13)
	v_add_u32_e32 v18, v18, v2
	s_waitcnt vmcnt(12)
	v_add_u32_e32 v18, v18, v3
	s_waitcnt vmcnt(11)
	v_add_u32_e32 v18, v18, v4
	s_waitcnt vmcnt(10)
	v_add_u32_e32 v18, v18, v5
	s_waitcnt vmcnt(9)
	v_add_u32_e32 v18, v18, v6
	s_waitcnt vmcnt(8)
	v_add_u32_e32 v18, v18, v7
	s_waitcnt vmcnt(7)
	v_add_u32_e32 v18, v18, v8
	s_waitcnt vmcnt(6)
	v_add_u32_e32 v18, v18, v9
	s_waitcnt vmcnt(5)
	v_add_u32_e32 v18, v18, v10
	s_waitcnt vmcnt(4)
	v_add_u32_e32 v18, v18, v11
	s_waitcnt vmcnt(3)
	v_add_u32_e32 v18, v18, v12
	s_waitcnt vmcnt(2)
	v_add_u32_e32 v18, v18, v13
	s_waitcnt vmcnt(1)
	v_add_u32_e32 v18, v18, v14
	s_waitcnt vmcnt(0)
	v_add_u32_e32 v18, v18, v15
	v_cmp_eq_u32_e32 vcc, s30, v18
	s_cbranch_vccnz .LBB0_243
	s_and_b32 s24, s31, 0xff
	s_cmp_eq_u32 s24, 0
	s_mov_b64 s[24:25], -1
	s_mov_b64 s[28:29], -1
	s_nop 0
	s_cbranch_scc0 .LBB0_248
	global_load_dword v18, v17, s[6:7] offset:512 sc1
	s_waitcnt vmcnt(0)
	v_cmp_eq_u32_e32 vcc, 0, v18
	s_cbranch_vccnz .LBB0_250
	s_mov_b64 s[28:29], 0

.LBB0_276:
	s_and_b32 s26, s30, 0xff
	s_mov_b64 s[24:25], -1
	s_cmp_lg_u32 s26, 0
	s_mov_b64 s[28:29], -1
	s_nop 0
	s_cbranch_scc1 .LBB0_279
	global_load_dword v2, v1, s[8:9] offset:512 sc1
	s_waitcnt vmcnt(0)
	v_cmp_eq_u32_e32 vcc, 0, v2
	s_cbranch_vccnz .LBB0_281
	s_mov_b64 s[28:29], 0
	s_mov_b64 s[26:27], -1

.LBB0_290:
	s_and_b32 s24, s28, 0xff
	s_mov_b64 s[22:23], -1
	s_cmp_lg_u32 s24, 0
	s_mov_b64 s[26:27], -1
	s_nop 0
	s_cbranch_scc1 .LBB0_293
	global_load_dword v2, v1, s[0:1] offset:512 sc1
	s_waitcnt vmcnt(0)
	v_cmp_eq_u32_e32 vcc, 0, v2
	s_cbranch_vccnz .LBB0_295
	s_mov_b64 s[26:27], 0
	s_mov_b64 s[24:25], -1

.LBB0_317:
	global_load_dword v16, v17, s[4:5] offset:1024 sc1
	global_load_dword v1, v17, s[4:5] offset:1280 sc1
	global_load_dword v2, v17, s[4:5] offset:1536 sc1
	global_load_dword v3, v17, s[4:5] offset:1792 sc1
	global_load_dword v4, v17, s[4:5] offset:2048 sc1
	global_load_dword v5, v17, s[4:5] offset:2304 sc1
	global_load_dword v6, v17, s[4:5] offset:2560 sc1
	global_load_dword v7, v17, s[4:5] offset:2816 sc1
	global_load_dword v8, v17, s[4:5] offset:3072 sc1
	global_load_dword v9, v17, s[4:5] offset:3328 sc1
	global_load_dword v10, v17, s[4:5] offset:3584 sc1
	global_load_dword v11, v17, s[4:5] offset:3840 sc1
	global_load_dword v12, v17, s[6:7] sc1
	global_load_dword v13, v17, s[8:9] sc1
	global_load_dword v14, v17, s[10:11] sc1
	global_load_dword v15, v17, s[12:13] sc1
	s_mov_b64 s[14:15], -1
	s_mov_b64 s[20:21], -1
	s_waitcnt vmcnt(14)
	v_add_u32_e32 v18, v1, v16
	s_waitcnt vmcnt(13)
	v_add_u32_e32 v18, v18, v2
	s_waitcnt vmcnt(12)
	v_add_u32_e32 v18, v18, v3
	s_waitcnt vmcnt(11)
	v_add_u32_e32 v18, v18, v4
	s_waitcnt vmcnt(10)
	v_add_u32_e32 v18, v18, v5
	s_waitcnt vmcnt(9)
	v_add_u32_e32 v18, v18, v6
	s_waitcnt vmcnt(8)
	v_add_u32_e32 v18, v18, v7
	s_waitcnt vmcnt(7)
	v_add_u32_e32 v18, v18, v8
	s_waitcnt vmcnt(6)
	v_add_u32_e32 v18, v18, v9
	s_waitcnt vmcnt(5)
	v_add_u32_e32 v18, v18, v10
	s_waitcnt vmcnt(4)
	v_add_u32_e32 v18, v18, v11
	s_waitcnt vmcnt(3)
	v_add_u32_e32 v18, v18, v12
	s_waitcnt vmcnt(2)
	v_add_u32_e32 v18, v18, v13
	s_waitcnt vmcnt(1)
	v_add_u32_e32 v18, v18, v14
	s_waitcnt vmcnt(0)
	v_add_u32_e32 v18, v18, v15
	v_cmp_eq_u32_e32 vcc, s24, v18
	s_cbranch_vccnz .LBB0_316
	s_and_b32 s14, s25, 0xff
	s_cmp_eq_u32 s14, 0
	s_mov_b64 s[14:15], -1
	s_mov_b64 s[22:23], -1
	s_nop 0
	s_cbranch_scc0 .LBB0_321
	global_load_dword v18, v17, s[4:5] offset:512 sc1
	s_waitcnt vmcnt(0)
	v_cmp_eq_u32_e32 vcc, 0, v18
	s_cbranch_vccnz .LBB0_323
	s_mov_b64 s[22:23], 0

.LBB0_333:
	s_and_b32 s24, s28, 0xff
	s_mov_b64 s[22:23], -1
	s_cmp_lg_u32 s24, 0
	s_mov_b64 s[26:27], -1
	s_nop 0
	s_cbranch_scc1 .LBB0_336
	global_load_dword v3, v1, s[6:7] offset:512 sc1
	s_waitcnt vmcnt(0)
	v_cmp_eq_u32_e32 vcc, 0, v3
	s_cbranch_vccnz .LBB0_338
	s_mov_b64 s[26:27], 0
	s_mov_b64 s[24:25], -1

.LBB0_350:
	s_and_b32 s22, s28, 0xff
	s_cmp_lg_u32 s22, 0
	s_mov_b64 s[24:25], -1
	s_nop 0
	s_cbranch_scc1 .LBB0_353
	global_load_dword v2, v1, s[12:13] sc1
	s_waitcnt vmcnt(0)
	v_cmp_eq_u32_e32 vcc, 0, v2
	s_cbranch_vccnz .LBB0_355
	s_mov_b64 s[24:25], 0
	s_mov_b64 s[22:23], -1
